# out phase: each workgroup takes 7 consecutive units of one mixer kind (unit remap) instead of a grid-strided mix
# speedup vs baseline: 1.0182x; 1.0182x over previous
; __global__ void __launch_bounds__(NT) mega(P p) {
;     ...
;     for (int u = blockIdx.x; u < 3 * NUNIT + (NUNIT - SB_M1); u += gridDim.x) {
;       if (u >= 3 * NUNIT) { sb_unit(p, SB_M1 + (u - 3 * NUNIT), smem); continue; }
;       const int kind = u / NUNIT, uu = u % NUNIT;
;       if (kind == 0) out_unit<0>(p, layer, uu, smem);
;       else if (kind == 1) out_unit<1>(p, layer, uu, smem);
;       else out_unit<2>(p, layer, uu, smem);
;     }
.LBB0_481:
	s_or_b64 exec, exec, s[0:1]
	v_readlane_b32 s0, v254, 44
	v_readlane_b32 s1, v254, 45
	s_andn2_b64 vcc, exec, s[0:1]
	s_waitcnt lgkmcnt(0)
	s_barrier
	s_cbranch_vccnz .LBB0_673
	v_readlane_b32 s0, v254, 61
	s_lshl_b32 s96, s0, 8
	v_readlane_b32 s12, v254, 25
	s_lshl_b64 s[0:1], s[96:97], 2
	v_readlane_b32 s24, v254, 37
	v_readlane_b32 s25, v254, 38
	s_add_u32 s60, s24, s0
	v_readlane_b32 s22, v254, 35
	s_addc_u32 s62, s25, s1
	v_readlane_b32 s23, v254, 36
	s_add_u32 s63, s22, s0
	v_readlane_b32 s14, v254, 27
	s_addc_u32 s64, s23, s1
	v_readlane_b32 s15, v254, 28
	s_add_u32 s65, s14, s0
	s_addc_u32 s66, s15, s1
	s_nop 0
	s_mul_i32 s33, s53, 7
	s_add_i32 s68, s53, 0x538
	s_cmpk_lt_i32 s33, 0x618
	s_cselect_b32 s33, s33, s68
	s_add_i32 s68, s33, 0xfffffbd0
	s_mov_b32 s58, 0
	v_readlane_b32 s13, v254, 26
	v_readlane_b32 s16, v254, 29
	v_readlane_b32 s17, v254, 30
	v_readlane_b32 s18, v254, 31
	v_readlane_b32 s19, v254, 32
	v_readlane_b32 s20, v254, 33
	v_readlane_b32 s21, v254, 34
	v_readlane_b32 s26, v254, 39
	v_readlane_b32 s27, v254, 40
	s_branch .LBB0_485

; __global__ void __launch_bounds__(NT) mega(P p) {
;     ...
;     for (int u = blockIdx.x; u < 3 * NUNIT + (NUNIT - SB_M1); u += gridDim.x) {
;       if (u >= 3 * NUNIT) { sb_unit(p, SB_M1 + (u - 3 * NUNIT), smem); continue; }
;       const int kind = u / NUNIT, uu = u % NUNIT;
;       if (kind == 0) out_unit<0>(p, layer, uu, smem);
;       else if (kind == 1) out_unit<1>(p, layer, uu, smem);
;       else out_unit<2>(p, layer, uu, smem);
;     }
.LBB0_484:
	s_add_i32 s33, s33, 1
	s_add_i32 s58, s58, 1
	s_cmpk_gt_i32 s33, 0x617
	s_cselect_b32 s57, 7, s58
	s_cmp_ge_i32 s57, 7
	v_mov_b32_e32 v208, v30
	global_store_dwordx2 v[4:5], v[0:1], off offset:96
	s_cbranch_scc1 .LBB0_672

;   __device__ __forceinline__ unsigned* cnt() const { unsigned o_ = (unsigned)(OFF_bar + 3456 * 4); asm volatile("" : "+s"(o_)); return (unsigned*)(ws + o_); }
;   __device__ __forceinline__ void exchange(const f32x4 (&acc)[2][2][4][2], const pg8::Unit& u, int wr, int wc, int fr, int fq, PG8_LAS float* ssq,
;                                            PG8_LAS float* rsv, int tid, float* ex, unsigned* cnt) const {
;     ...
;     if (tid == 0) {
;       __builtin_amdgcn_fence(__ATOMIC_RELEASE, "agent");
;       asm volatile("s_waitcnt vmcnt(0)" ::: "memory");
;       __hip_atomic_fetch_add(cnt + u.pm, 1u, __ATOMIC_RELAXED, __HIP_MEMORY_SCOPE_AGENT);
;       unsigned sp = 0;
;       while (__hip_atomic_load(cnt + u.pm, __ATOMIC_RELAXED, __HIP_MEMORY_SCOPE_AGENT) < 4u) { __builtin_amdgcn_s_sleep(1); if (++sp > (1u << 22)) break; }
.LBB0_828:
	s_or_b64 exec, exec, s[0:1]
	s_waitcnt vmcnt(0)
	v_cmp_eq_u32_e64 s[6:7], 0, v154
	s_barrier
	s_and_saveexec_b64 s[0:1], s[6:7]
	s_cbranch_execz .LBB0_839
	s_add_u32 s17, s76, s37
	s_addc_u32 s18, s77, 0
	s_lshl_b64 s[12:13], s[96:97], 2
	s_add_u32 s19, s17, s12
	s_addc_u32 s20, s18, s13
	s_ashr_i32 s17, s16, 31
	s_lshl_b64 s[12:13], s[16:17], 2
	s_add_u32 s18, s19, s12
	s_addc_u32 s19, s20, s13
	s_mov_b64 s[20:21], exec
	buffer_wbl2 sc1
	s_waitcnt vmcnt(0)
	s_waitcnt vmcnt(0)
	v_mbcnt_lo_u32_b32 v128, s20, 0
	v_mbcnt_hi_u32_b32 v128, s21, v128
	v_cmp_eq_u32_e32 vcc, 0, v128
	s_and_saveexec_b64 s[22:23], vcc
	s_cbranch_execz .LBB0_831
	s_bcnt1_i32_b64 s12, s[20:21]
	v_mov_b32_e32 v128, s12
	global_atomic_add v139, v128, s[18:19]

;   __device__ __forceinline__ unsigned* cnt() const { unsigned o_ = (unsigned)(OFF_bar + 3456 * 4); asm volatile("" : "+s"(o_)); return (unsigned*)(ws + o_); }
;   __device__ __forceinline__ void exchange(const f32x4 (&acc)[2][2][4][2], const pg8::Unit& u, int wr, int wc, int fr, int fq, PG8_LAS float* ssq,
;                                            PG8_LAS float* rsv, int tid, float* ex, unsigned* cnt) const {
;     ...
;     if (tid == 0) {
;       __builtin_amdgcn_fence(__ATOMIC_RELEASE, "agent");
;       asm volatile("s_waitcnt vmcnt(0)" ::: "memory");
;       __hip_atomic_fetch_add(cnt + u.pm, 1u, __ATOMIC_RELAXED, __HIP_MEMORY_SCOPE_AGENT);
;       unsigned sp = 0;
;       while (__hip_atomic_load(cnt + u.pm, __ATOMIC_RELAXED, __HIP_MEMORY_SCOPE_AGENT) < 4u) { __builtin_amdgcn_s_sleep(1); if (++sp > (1u << 22)) break; }
.LBB0_859:
	s_or_b64 exec, exec, s[0:1]
	s_waitcnt vmcnt(0)
	s_barrier
	s_and_saveexec_b64 s[0:1], s[6:7]
	s_cbranch_execz .LBB0_870
	s_add_u32 s6, s76, s31
	s_addc_u32 s7, s77, 0
	s_lshl_b64 s[2:3], s[96:97], 2
	s_add_u32 s6, s6, s2
	s_addc_u32 s7, s7, s3
	s_ashr_i32 s17, s16, 31
	s_lshl_b64 s[2:3], s[16:17], 2
	s_add_u32 s2, s6, s2
	s_addc_u32 s3, s7, s3
	s_mov_b64 s[6:7], exec
	buffer_wbl2 sc1
	s_waitcnt vmcnt(0)
	s_waitcnt vmcnt(0)
	v_mbcnt_lo_u32_b32 v0, s6, 0
	v_mbcnt_hi_u32_b32 v0, s7, v0
	v_cmp_eq_u32_e32 vcc, 0, v0
	s_and_saveexec_b64 s[18:19], vcc
	s_cbranch_execz .LBB0_862
	s_bcnt1_i32_b64 s6, s[6:7]
	v_mov_b32_e32 v0, s6
	global_atomic_add v139, v0, s[2:3] offset:256

;   __device__ __forceinline__ unsigned* cnt() const { unsigned o_ = (unsigned)(OFF_bar + 3456 * 4); asm volatile("" : "+s"(o_)); return (unsigned*)(ws + o_); }
;   __device__ __forceinline__ void exchange(const f32x4 (&acc)[2][2][4][2], const pg8::Unit& u, int wr, int wc, int fr, int fq, PG8_LAS float* ssq,
;                                            PG8_LAS float* rsv, int tid, float* ex, unsigned* cnt) const {
;     ...
;     if (tid == 0) {
;       __builtin_amdgcn_fence(__ATOMIC_RELEASE, "agent");
;       asm volatile("s_waitcnt vmcnt(0)" ::: "memory");
;       __hip_atomic_fetch_add(cnt + u.pm, 1u, __ATOMIC_RELAXED, __HIP_MEMORY_SCOPE_AGENT);
;       unsigned sp = 0;
;       while (__hip_atomic_load(cnt + u.pm, __ATOMIC_RELAXED, __HIP_MEMORY_SCOPE_AGENT) < 4u) { __builtin_amdgcn_s_sleep(1); if (++sp > (1u << 22)) break; }
.LBB0_1099:
	s_or_b64 exec, exec, s[0:1]
	s_waitcnt vmcnt(0)
	v_cmp_eq_u32_e64 s[8:9], 0, v154
	s_barrier
	s_and_saveexec_b64 s[0:1], s[8:9]
	s_cbranch_execz .LBB0_1110
	s_add_u32 s17, s76, s17
	s_addc_u32 s18, s77, 0
	s_lshl_b64 s[12:13], s[96:97], 2
	s_add_u32 s19, s17, s12
	s_addc_u32 s20, s18, s13
	s_ashr_i32 s17, s16, 31
	s_lshl_b64 s[12:13], s[16:17], 2
	s_add_u32 s18, s19, s12
	s_addc_u32 s19, s20, s13
	s_mov_b64 s[20:21], exec
	buffer_wbl2 sc1
	s_waitcnt vmcnt(0)
	s_waitcnt vmcnt(0)
	v_mbcnt_lo_u32_b32 v128, s20, 0
	v_mbcnt_hi_u32_b32 v128, s21, v128
	v_cmp_eq_u32_e32 vcc, 0, v128
	s_and_saveexec_b64 s[22:23], vcc
	s_cbranch_execz .LBB0_1102
	s_bcnt1_i32_b64 s12, s[20:21]
	v_mov_b32_e32 v128, s12
	global_atomic_add v139, v128, s[18:19] offset:512

;   __device__ __forceinline__ unsigned* cnt() const { unsigned o_ = (unsigned)(OFF_bar + 3456 * 4); asm volatile("" : "+s"(o_)); return (unsigned*)(ws + o_); }
;   __device__ __forceinline__ void exchange(const f32x4 (&acc)[2][2][4][2], const pg8::Unit& u, int wr, int wc, int fr, int fq, PG8_LAS float* ssq,
;                                            PG8_LAS float* rsv, int tid, float* ex, unsigned* cnt) const {
;     ...
;     if (tid == 0) {
;       __builtin_amdgcn_fence(__ATOMIC_RELEASE, "agent");
;       asm volatile("s_waitcnt vmcnt(0)" ::: "memory");
;       __hip_atomic_fetch_add(cnt + u.pm, 1u, __ATOMIC_RELAXED, __HIP_MEMORY_SCOPE_AGENT);
;       unsigned sp = 0;
;       while (__hip_atomic_load(cnt + u.pm, __ATOMIC_RELAXED, __HIP_MEMORY_SCOPE_AGENT) < 4u) { __builtin_amdgcn_s_sleep(1); if (++sp > (1u << 22)) break; }
.LBB0_1130:
	s_or_b64 exec, exec, s[0:1]
	s_waitcnt vmcnt(0)
	s_barrier
	s_and_saveexec_b64 s[0:1], s[8:9]
	s_cbranch_execz .LBB0_1141
	s_add_u32 s8, s76, s27
	s_addc_u32 s9, s77, 0
	s_lshl_b64 s[4:5], s[96:97], 2
	s_add_u32 s8, s8, s4
	s_addc_u32 s9, s9, s5
	s_ashr_i32 s17, s16, 31
	s_lshl_b64 s[4:5], s[16:17], 2
	s_add_u32 s4, s8, s4
	s_addc_u32 s5, s9, s5
	s_mov_b64 s[8:9], exec
	buffer_wbl2 sc1
	s_waitcnt vmcnt(0)
	s_waitcnt vmcnt(0)
	v_mbcnt_lo_u32_b32 v0, s8, 0
	v_mbcnt_hi_u32_b32 v0, s9, v0
	v_cmp_eq_u32_e32 vcc, 0, v0
	s_and_saveexec_b64 s[18:19], vcc
	s_cbranch_execz .LBB0_1133
	s_bcnt1_i32_b64 s8, s[8:9]
	v_mov_b32_e32 v0, s8
	global_atomic_add v139, v0, s[4:5] offset:768

;   __device__ __forceinline__ unsigned* cnt() const { unsigned o_ = (unsigned)(OFF_bar + 3456 * 4); asm volatile("" : "+s"(o_)); return (unsigned*)(ws + o_); }
;   __device__ __forceinline__ void exchange(const f32x4 (&acc)[2][2][4][2], const pg8::Unit& u, int wr, int wc, int fr, int fq, PG8_LAS float* ssq,
;                                            PG8_LAS float* rsv, int tid, float* ex, unsigned* cnt) const {
;     ...
;     if (tid == 0) {
;       __builtin_amdgcn_fence(__ATOMIC_RELEASE, "agent");
;       asm volatile("s_waitcnt vmcnt(0)" ::: "memory");
;       __hip_atomic_fetch_add(cnt + u.pm, 1u, __ATOMIC_RELAXED, __HIP_MEMORY_SCOPE_AGENT);
;       unsigned sp = 0;
;       while (__hip_atomic_load(cnt + u.pm, __ATOMIC_RELAXED, __HIP_MEMORY_SCOPE_AGENT) < 4u) { __builtin_amdgcn_s_sleep(1); if (++sp > (1u << 22)) break; }
.LBB0_1190:
	s_or_b64 exec, exec, s[4:5]
	s_waitcnt vmcnt(0)
	v_cmp_eq_u32_e32 vcc, 0, v128
	s_barrier
	s_and_saveexec_b64 s[4:5], vcc
	s_cbranch_execz .LBB0_1201
	s_add_u32 s12, s76, s9
	s_addc_u32 s13, s77, 0
	s_ashr_i32 s9, s8, 31
	s_mov_b64 s[16:17], exec
	buffer_wbl2 sc1
	s_waitcnt vmcnt(0)
	s_waitcnt vmcnt(0)
	s_lshl_b64 s[6:7], s[8:9], 2
	v_mbcnt_lo_u32_b32 v131, s16, 0
	s_add_u32 s6, s12, s6
	v_mbcnt_hi_u32_b32 v131, s17, v131
	s_addc_u32 s7, s13, s7
	v_cmp_eq_u32_e32 vcc, 0, v131
	s_and_saveexec_b64 s[18:19], vcc
	s_cbranch_execz .LBB0_1193
	s_bcnt1_i32_b64 s9, s[16:17]
	v_mov_b32_e32 v131, s9
	global_atomic_add v139, v131, s[6:7] offset:3584
